# p0_stagger_transposes_first_half
# speedup vs baseline: 1.0974x; 1.0159x over previous
.LBB0_15:
	v_mov_b32_e32 v0, v181
	s_cmpk_gt_i32 s2, 0x255f
	v_mbcnt_lo_u32_b32 v183, -1, 0
	s_cbranch_scc1 .LBB0_44
	v_lshlrev_b32_e32 v1, 2, v0
	v_and_b32_e32 v12, 0xfc, v1
	v_max_i32_e32 v1, 0xf00, v0
	v_mov_b32_e32 v3, 0
	v_lshlrev_b32_e32 v2, 1, v12
	v_sub_u32_e32 v1, v1, v0
	v_lshl_add_u64 v[4:5], s[50:51], 0, v[2:3]
	v_lshlrev_b32_e32 v2, 2, v12
	v_add_u32_e32 v1, 0xff, v1
	s_waitcnt lgkmcnt(0)
	v_lshl_add_u64 v[10:11], s[62:63], 0, v[2:3]
	v_lshrrev_b32_e32 v2, 8, v1
	v_add_u32_e32 v13, 1, v2
	v_add_u32_e32 v2, -1, v2
	v_lshrrev_b32_e32 v14, 1, v2
	v_and_b32_e32 v6, 63, v0
	v_add_u32_e32 v14, 1, v14
	v_and_b32_e32 v15, 0x1fffffe, v13
	v_mbcnt_hi_u32_b32 v22, -1, v183
	s_movk_i32 s0, 0x1000
	v_lshlrev_b32_e32 v8, 2, v6
	s_movk_i32 s4, 0xff
	v_and_b32_e32 v19, 3, v14
	v_cmp_ne_u32_e64 s[10:11], v13, v15
	v_and_b32_e32 v13, 64, v22
	v_ashrrev_i32_e32 v7, 6, v0
	v_cmp_gt_i32_e64 s[0:1], s0, v0
	v_lshl_or_b32 v9, v6, 8, v8
	v_cmp_lt_u32_e64 s[4:5], s4, v1
	v_lshl_add_u32 v18, v15, 8, v0
	v_add_u32_e32 v1, 0x100, v0
	v_cmp_lt_u32_e64 s[6:7], 5, v2
	v_and_b32_e32 v20, -4, v14
	v_cmp_ne_u32_e64 s[8:9], 0, v19
	s_movk_i32 s62, 0xdfc0
	s_movk_i32 s63, 0x1010
	s_movk_i32 s68, 0x4040
	s_movk_i32 s69, 0x104
	s_movk_i32 s70, 0xeff
	s_mov_b32 s71, 0x10200000
	s_mov_b32 s72, 0x8000
	v_lshlrev_b32_e32 v12, 2, v12
	v_mov_b32_e32 v21, 0x358637bd
	s_mov_b32 s73, 0x800000
	v_lshlrev_b32_e32 v2, 1, v6
	v_add_u32_e32 v23, 64, v13
	v_xor_b32_e32 v24, 32, v22
	v_xor_b32_e32 v25, 16, v22
	v_xor_b32_e32 v26, 8, v22
	v_xor_b32_e32 v27, 4, v22
	v_xor_b32_e32 v28, 2, v22
	v_xor_b32_e32 v29, 1, v22
	s_mov_b32 s74, s2
	s_mov_b32 s99, 0
	s_cmpk_eq_i32 s22, 0x200
	s_cbranch_scc0 .Lrms_entry
	s_cmpk_lt_u32 s2, 0x100
	s_cbranch_scc1 .Lrms_entry
	s_mov_b32 s99, 1
	s_add_i32 s74, s2, 0x2000
	s_branch .Ltr_entry
.Lrms_entry:
	s_cmpk_lt_i32 s74, 0x2040
	s_cbranch_scc0 .Lrms_done
	v_and_b32_e32 v64, 63, v181
	v_lshrrev_b32_e32 v65, 6, v181
	v_lshlrev_b32_e32 v66, 4, v64
	v_lshlrev_b32_e32 v67, 3, v64
	v_lshrrev_b32_e32 v144, 3, v64
	s_mov_b32 s81, 0x204000
	v_mul_lo_u32 v144, v144, s81
	v_and_b32_e32 v145, 7, v64
	v_lshl_add_u32 v144, v145, 3, v144
	global_load_dwordx4 v[68:71], v[10:11], off
	global_load_dwordx4 v[72:75], v[10:11], off offset:1024
	global_load_dwordx4 v[76:79], v[10:11], off offset:2048
	global_load_dwordx4 v[80:83], v[10:11], off offset:3072
	s_cmpk_lt_u32 s74, 0x2000
	s_cselect_b32 s84, s52, s54
	s_cselect_b32 s85, s53, s55
	s_cselect_b32 s86, 0, 0x2000
	s_sub_u32 s86, s74, s86
	v_lshl_add_u32 v84, s86, 2, v65
	v_lshl_add_u32 v84, v84, 12, v66
	v_lshl_add_u32 v86, s74, 2, v65
	v_lshl_add_u32 v136, v86, 6, v144
	v_add_u32_e32 v137, 0x1020000, v136
	v_add_u32_e32 v138, 0x1020000, v137
	v_add_u32_e32 v139, 0x1020000, v138
	global_load_dwordx4 v[88:91], v84, s[84:85] nt
	global_load_dwordx4 v[92:95], v84, s[84:85] offset:1024 nt
	global_load_dwordx4 v[96:99], v84, s[84:85] offset:2048 nt
	global_load_dwordx4 v[100:103], v84, s[84:85] offset:3072 nt
	s_add_i32 s80, s74, s22
	s_cmpk_lt_i32 s80, 0x2040
	s_cbranch_scc0 .Lrms_last0
	s_cmpk_lt_u32 s80, 0x2000
	s_cselect_b32 s84, s52, s54
	s_cselect_b32 s85, s53, s55
	s_cselect_b32 s86, 0, 0x2000
	s_sub_u32 s86, s80, s86
	v_lshl_add_u32 v85, s86, 2, v65
	v_lshl_add_u32 v85, v85, 12, v66
	v_lshl_add_u32 v87, s80, 2, v65
	v_lshl_add_u32 v140, v87, 6, v144
	v_add_u32_e32 v141, 0x1020000, v140
	v_add_u32_e32 v142, 0x1020000, v141
	v_add_u32_e32 v143, 0x1020000, v142
	global_load_dwordx4 v[104:107], v85, s[84:85] nt
	global_load_dwordx4 v[108:111], v85, s[84:85] offset:1024 nt
	global_load_dwordx4 v[112:115], v85, s[84:85] offset:2048 nt
	global_load_dwordx4 v[116:119], v85, s[84:85] offset:3072 nt
	s_waitcnt vmcnt(4)
	v_mul_f32_e32 v120, v88, v88
	v_fmac_f32_e32 v120, v89, v89
	v_fmac_f32_e32 v120, v90, v90
	v_fmac_f32_e32 v120, v91, v91
	v_fmac_f32_e32 v120, v92, v92
	v_fmac_f32_e32 v120, v93, v93
	v_fmac_f32_e32 v120, v94, v94
	v_fmac_f32_e32 v120, v95, v95
	v_fmac_f32_e32 v120, v96, v96
	v_fmac_f32_e32 v120, v97, v97
	v_fmac_f32_e32 v120, v98, v98
	v_fmac_f32_e32 v120, v99, v99
	v_fmac_f32_e32 v120, v100, v100
	v_fmac_f32_e32 v120, v101, v101
	v_fmac_f32_e32 v120, v102, v102
	v_fmac_f32_e32 v120, v103, v103
	s_nop 1
	v_add_f32_dpp v120, v120, v120 quad_perm:[1,0,3,2] row_mask:0xf bank_mask:0xf
	s_nop 1
	v_add_f32_dpp v120, v120, v120 quad_perm:[2,3,0,1] row_mask:0xf bank_mask:0xf
	s_nop 1
	v_add_f32_dpp v120, v120, v120 row_half_mirror row_mask:0xf bank_mask:0xf
	s_nop 1
	v_add_f32_dpp v120, v120, v120 row_mirror row_mask:0xf bank_mask:0xf
	s_nop 1
	v_readlane_b32 s87, v120, 0
	v_readlane_b32 s88, v120, 16
	v_readlane_b32 s89, v120, 32
	v_readlane_b32 s90, v120, 48
	s_nop 1
	v_mov_b32_e32 v121, s87
	v_add_f32_e32 v121, s88, v121
	v_add_f32_e32 v121, s89, v121
	v_add_f32_e32 v121, s90, v121
	v_mov_b32_e32 v122, 0x358637bd
	v_fmamk_f32 v121, v121, 0x3a800000, v122
	v_rsq_f32_e32 v121, v121
	s_nop 0
	v_mul_f32_e32 v88, v88, v121
	v_mul_f32_e32 v89, v89, v121
	v_mul_f32_e32 v90, v90, v121
	v_mul_f32_e32 v91, v91, v121
	v_mul_f32_e32 v92, v92, v121
	v_mul_f32_e32 v93, v93, v121
	v_mul_f32_e32 v94, v94, v121
	v_mul_f32_e32 v95, v95, v121
	v_mul_f32_e32 v96, v96, v121
	v_mul_f32_e32 v97, v97, v121
	v_mul_f32_e32 v98, v98, v121
	v_mul_f32_e32 v99, v99, v121
	v_mul_f32_e32 v100, v100, v121
	v_mul_f32_e32 v101, v101, v121
	v_mul_f32_e32 v102, v102, v121
	v_mul_f32_e32 v103, v103, v121
	v_mul_f32_e32 v88, v68, v88
	v_mul_f32_e32 v89, v69, v89
	v_mul_f32_e32 v90, v70, v90
	v_mul_f32_e32 v91, v71, v91
	v_mul_f32_e32 v92, v72, v92
	v_mul_f32_e32 v93, v73, v93
	v_mul_f32_e32 v94, v74, v94
	v_mul_f32_e32 v95, v75, v95
	v_mul_f32_e32 v96, v76, v96
	v_mul_f32_e32 v97, v77, v97
	v_mul_f32_e32 v98, v78, v98
	v_mul_f32_e32 v99, v79, v99
	v_mul_f32_e32 v100, v80, v100
	v_mul_f32_e32 v101, v81, v101
	v_mul_f32_e32 v102, v82, v102
	v_mul_f32_e32 v103, v83, v103
	v_cvt_pk_bf16_f32 v124, v88, v89
	v_cvt_pk_bf16_f32 v125, v90, v91
	v_cvt_pk_bf16_f32 v126, v92, v93
	v_cvt_pk_bf16_f32 v127, v94, v95
	v_cvt_pk_bf16_f32 v128, v96, v97
	v_cvt_pk_bf16_f32 v129, v98, v99
	v_cvt_pk_bf16_f32 v130, v100, v101
	v_cvt_pk_bf16_f32 v131, v102, v103
	global_store_dwordx2 v136, v[124:125], s[50:51]
	global_store_dwordx2 v137, v[126:127], s[50:51]
	global_store_dwordx2 v138, v[128:129], s[50:51]
	global_store_dwordx2 v139, v[130:131], s[50:51]
	s_mov_b32 s74, s80

.Lrms_done:
	s_cmp_eq_u32 s99, 1
	s_cbranch_scc1 .LBB0_44
	s_cmpk_lt_i32 s74, 0x2560
	s_cbranch_scc0 .LBB0_44
.Ltr_entry:
	v_and_b32_e32 v64, 63, v181
	v_lshrrev_b32_e32 v65, 6, v181
	v_lshrrev_b32_e32 v88, 2, v181
	v_and_b32_e32 v89, 3, v181
	v_mul_u32_u24_e32 v71, 0x41, v65
	v_add_lshl_u32 v71, v71, v64, 2
	v_mul_u32_u24_e32 v90, 0x820, v89
	v_lshl_add_u32 v90, v88, 2, v90
.Ltr_loop:
	s_sub_i32 s80, s74, 0x2040
	s_movk_i32 s86, 0x400
	s_mov_b32 s92, 0x10a40000
	s_cmpk_lt_u32 s80, 0x420
	s_cselect_b32 s84, s64, s46
	s_cselect_b32 s85, s65, s47
	s_cselect_b32 s86, 0x1010, s86
	s_cselect_b32 s92, 0x10200000, s92
	s_cselect_b64 s[88:89], -1, 0
	s_cselect_b32 s96, 6, 11
	s_movk_i32 s97, 0x40
	s_cselect_b32 s97, 0x42000, s97
	s_movk_i32 s98, 0x80
	s_cselect_b32 s98, 0x84000, s98
	s_cselect_b32 s81, 0, 0x420
	s_sub_u32 s80, s80, s81
	s_lshr_b32 s82, s80, 4
	s_and_b32 s83, s80, 15
	s_lshl_b32 s87, s86, 4
	s_add_u32 s92, s20, s92
	s_addc_u32 s93, s21, 0
	v_lshl_add_u32 v66, s82, 6, v64
	v_add_u32_e32 v67, 16, v66
	v_add_u32_e32 v68, 0xfffff800, v66
	v_cmp_gt_u32_e32 vcc, 0x800, v66
	s_nop 1
	v_cndmask_b32_e32 v69, v67, v66, vcc
	v_cmp_gt_u32_e32 vcc, 0x1000, v66
	s_nop 1
	v_cndmask_b32_e32 v69, v68, v69, vcc
	v_cmp_gt_u32_e64 s[90:91], s86, v66
	v_cndmask_b32_e64 v69, v66, v69, s[88:89]
	s_orn2_b64 s[90:91], s[90:91], s[88:89]
	v_lshl_add_u32 v70, s83, 6, v65
	v_mul_lo_u32 v70, v70, s86
	v_add_lshl_u32 v70, v70, v69, 2
	v_mov_b32_e32 v72, 0
	v_mov_b32_e32 v73, 0
	v_mov_b32_e32 v74, 0
	v_mov_b32_e32 v75, 0
	v_mov_b32_e32 v76, 0
	v_mov_b32_e32 v77, 0
	v_mov_b32_e32 v78, 0
	v_mov_b32_e32 v79, 0
	v_mov_b32_e32 v80, 0
	v_mov_b32_e32 v81, 0
	v_mov_b32_e32 v82, 0
	v_mov_b32_e32 v83, 0
	v_mov_b32_e32 v84, 0
	v_mov_b32_e32 v85, 0
	v_mov_b32_e32 v86, 0
	v_mov_b32_e32 v87, 0
	s_mov_b64 vcc, exec
	s_and_b64 exec, exec, s[90:91]
	global_load_dword v72, v70, s[84:85] nt
	v_add_u32_e32 v70, s87, v70
	global_load_dword v73, v70, s[84:85] nt
	v_add_u32_e32 v70, s87, v70
	global_load_dword v74, v70, s[84:85] nt
	v_add_u32_e32 v70, s87, v70
	global_load_dword v75, v70, s[84:85] nt
	v_add_u32_e32 v70, s87, v70
	global_load_dword v76, v70, s[84:85] nt
	v_add_u32_e32 v70, s87, v70
	global_load_dword v77, v70, s[84:85] nt
	v_add_u32_e32 v70, s87, v70
	global_load_dword v78, v70, s[84:85] nt
	v_add_u32_e32 v70, s87, v70
	global_load_dword v79, v70, s[84:85] nt
	v_add_u32_e32 v70, s87, v70
	global_load_dword v80, v70, s[84:85] nt
	v_add_u32_e32 v70, s87, v70
	global_load_dword v81, v70, s[84:85] nt
	v_add_u32_e32 v70, s87, v70
	global_load_dword v82, v70, s[84:85] nt
	v_add_u32_e32 v70, s87, v70
	global_load_dword v83, v70, s[84:85] nt
	v_add_u32_e32 v70, s87, v70
	global_load_dword v84, v70, s[84:85] nt
	v_add_u32_e32 v70, s87, v70
	global_load_dword v85, v70, s[84:85] nt
	v_add_u32_e32 v70, s87, v70
	global_load_dword v86, v70, s[84:85] nt
	v_add_u32_e32 v70, s87, v70
	global_load_dword v87, v70, s[84:85] nt
	s_mov_b64 exec, vcc
	s_barrier
	s_waitcnt vmcnt(0)
	ds_write_b32 v71, v72
	ds_write_b32 v71, v73 offset:1040
	ds_write_b32 v71, v74 offset:2080
	ds_write_b32 v71, v75 offset:3120
	ds_write_b32 v71, v76 offset:4160
	ds_write_b32 v71, v77 offset:5200
	ds_write_b32 v71, v78 offset:6240
	ds_write_b32 v71, v79 offset:7280
	ds_write_b32 v71, v80 offset:8320
	ds_write_b32 v71, v81 offset:9360
	ds_write_b32 v71, v82 offset:10400
	ds_write_b32 v71, v83 offset:11440
	ds_write_b32 v71, v84 offset:12480
	ds_write_b32 v71, v85 offset:13520
	ds_write_b32 v71, v86 offset:14560
	ds_write_b32 v71, v87 offset:15600
	s_waitcnt lgkmcnt(0)
	s_barrier
	ds_read_b32 v72, v90
	ds_read_b32 v73, v90 offset:260
	ds_read_b32 v74, v90 offset:520
	ds_read_b32 v75, v90 offset:780
	ds_read_b32 v76, v90 offset:1040
	ds_read_b32 v77, v90 offset:1300
	ds_read_b32 v78, v90 offset:1560
	ds_read_b32 v79, v90 offset:1820
	ds_read_b32 v80, v90 offset:8320
	ds_read_b32 v81, v90 offset:8580
	ds_read_b32 v82, v90 offset:8840
	ds_read_b32 v83, v90 offset:9100
	ds_read_b32 v84, v90 offset:9360
	ds_read_b32 v85, v90 offset:9620
	ds_read_b32 v86, v90 offset:9880
	ds_read_b32 v87, v90 offset:10140
	v_lshl_add_u32 v91, s82, 6, v88
	v_lshlrev_b32_e32 v91, s96, v91
	v_lshl_add_u32 v91, v89, 4, v91
	s_mul_i32 s81, s83, s98
	v_add_u32_e32 v91, s81, v91
	v_add_u32_e32 v100, s97, v91
	s_waitcnt lgkmcnt(0)
	v_cvt_pk_bf16_f32 v92, v72, v73
	v_cvt_pk_bf16_f32 v93, v74, v75
	v_cvt_pk_bf16_f32 v94, v76, v77
	v_cvt_pk_bf16_f32 v95, v78, v79
	v_cvt_pk_bf16_f32 v96, v80, v81
	v_cvt_pk_bf16_f32 v97, v82, v83
	v_cvt_pk_bf16_f32 v98, v84, v85
	v_cvt_pk_bf16_f32 v99, v86, v87
	global_store_dwordx4 v91, v[92:95], s[92:93]
	global_store_dwordx4 v100, v[96:99], s[92:93]
	s_add_i32 s74, s74, s22
	s_cmpk_lt_i32 s74, 0x2560
	s_cbranch_scc1 .Ltr_loop
	s_cmp_eq_u32 s99, 1
	s_cbranch_scc0 .LBB0_44
	s_mov_b32 s74, s2
	s_branch .Lrms_entry
	s_branch .LBB0_18
